# L2 GEMM tile order column-major inside each XCD band (12 row tiles share one B tile), on top of the conv rewrite
# baseline (speedup 1.0000x reference)
.LBB0_259:
	s_cmpk_eq_u32 s21, 0x15c
	s_cbranch_scc0 .Lg2_oldmap
	s_mul_hi_u32 s3, s6, 0xaaaaaaab
	s_lshr_b32 s3, s3, 3
	s_mul_i32 s4, s3, 12
	s_sub_i32 s4, s6, s4
	s_lshl_b32 s2, s3, 7
	s_mul_hi_u32 s3, s22, 0x8d3dcb09
	s_lshr_b32 s3, s3, 4
	s_add_i32 s3, s3, s4
	s_lshl_b32 s3, s3, 7
	s_branch .Lg2_map_done

.Lg2_map_done:
	s_lshl_b32 s62, s3, 11
	s_add_u32 s54, s82, s62
	s_addc_u32 s55, s83, 0
	s_add_u32 s54, s54, 0x3000000
	s_addc_u32 s55, s55, 0
	s_lshl_b32 s62, s2, 11
	s_add_u32 s56, s60, s62
	s_addc_u32 s57, s61, 0
	s_add_u32 m0, s58, 0x0
	s_nop 0
	global_load_lds_dwordx4 v152, s[54:55]
	s_add_u32 m0, m0, 0x400
	s_nop 0
	global_load_lds_dwordx4 v153, s[54:55]
	s_add_u32 m0, m0, 0x400
	s_nop 0
	global_load_lds_dwordx4 v154, s[54:55]
	s_add_u32 m0, m0, 0x400
	s_nop 0
	global_load_lds_dwordx4 v155, s[54:55]
	s_add_u32 m0, m0, 0x3400
	s_nop 0
	global_load_lds_dwordx4 v152, s[56:57]
	s_add_u32 m0, m0, 0x400
	s_nop 0
	global_load_lds_dwordx4 v153, s[56:57]
	s_add_u32 m0, m0, 0x400
	s_nop 0
	global_load_lds_dwordx4 v154, s[56:57]
	s_add_u32 m0, m0, 0x400
	s_nop 0
	global_load_lds_dwordx4 v155, s[56:57]
	v_mov_b32_e32 v60, 0
	v_mov_b32_e32 v61, v60
	v_mov_b32_e32 v62, v60
	v_mov_b32_e32 v63, v60
	v_mov_b32_e32 v40, v60
	v_mov_b32_e32 v41, v60
	v_mov_b32_e32 v42, v60
	v_mov_b32_e32 v43, v60
	v_mov_b32_e32 v44, v60
	v_mov_b32_e32 v45, v60
	v_mov_b32_e32 v46, v60
	v_mov_b32_e32 v47, v60
	v_mov_b32_e32 v48, v60
	v_mov_b32_e32 v49, v60
	v_mov_b32_e32 v50, v60
	v_mov_b32_e32 v51, v60
	v_mov_b32_e32 v52, v60
	v_mov_b32_e32 v53, v60
	v_mov_b32_e32 v54, v60
	v_mov_b32_e32 v55, v60
	v_mov_b32_e32 v56, v60
	v_mov_b32_e32 v57, v60
	v_mov_b32_e32 v58, v60
	v_mov_b32_e32 v59, v60
	v_mov_b32_e32 v16, v60
	v_mov_b32_e32 v17, v60
	v_mov_b32_e32 v18, v60
	v_mov_b32_e32 v19, v60
	v_mov_b32_e32 v12, v60
	v_mov_b32_e32 v13, v60
	v_mov_b32_e32 v14, v60
	v_mov_b32_e32 v15, v60
	v_mov_b32_e32 v20, v60
	v_mov_b32_e32 v21, v60
	v_mov_b32_e32 v22, v60
	v_mov_b32_e32 v23, v60
	v_mov_b32_e32 v0, v60
	v_mov_b32_e32 v1, v60
	v_mov_b32_e32 v2, v60
	v_mov_b32_e32 v3, v60
	v_mov_b32_e32 v4, v60
	v_mov_b32_e32 v5, v60
	v_mov_b32_e32 v6, v60
	v_mov_b32_e32 v7, v60
	v_mov_b32_e32 v8, v60
	v_mov_b32_e32 v9, v60
	v_mov_b32_e32 v10, v60
	v_mov_b32_e32 v11, v60
	v_mov_b32_e32 v24, v60
	v_mov_b32_e32 v25, v60
	v_mov_b32_e32 v26, v60
	v_mov_b32_e32 v27, v60
	v_mov_b32_e32 v28, v60
	v_mov_b32_e32 v29, v60
	v_mov_b32_e32 v30, v60
	v_mov_b32_e32 v31, v60
	v_mov_b32_e32 v32, v60
	v_mov_b32_e32 v33, v60
	v_mov_b32_e32 v34, v60
	v_mov_b32_e32 v35, v60
	v_mov_b32_e32 v36, v60
	v_mov_b32_e32 v37, v60
	v_mov_b32_e32 v38, v60
	v_mov_b32_e32 v39, v60
	s_mov_b32 s59, 8
	s_waitcnt vmcnt(0)
	s_barrier
